# mLSTM chunk outputs: o/z gate loads of all four value tiles issued together
# baseline (speedup 1.0000x reference)
; #define LAS __attribute__((address_space(3)))
; __device__ __forceinline__ float bflo(unsigned u) { return __uint_as_float(u << 16); }
; __device__ __forceinline__ float bfhi(unsigned u) { return __uint_as_float(u & 0xffff0000u); }
; __device__ __forceinline__ unsigned cvt_pk_bf16(float lo, float hi) { unsigned r; asm volatile("s_nop 0\n\tv_cvt_pk_bf16_f32 %0, %1, %2" : "=v"(r) : "v"(lo), "v"(hi)); return r; }
; __device__ __forceinline__ void c3_item(KP P, int l, int item, LAS unsigned char* lds) {
;     ...
;     { const int tsub = wave >> 1, t = tsub * 16 + fr;
;       const float wi = wil[t], den = wi * nql[t] + rsl[t * 2] + rsl[t * 2 + 1];
;       const float inv = 1.f / fmaxf(fabsf(den), __expf(-mtl[t]));
;       bf16x8 qb[2], sb[2];
; #pragma unroll
;       for (int ks = 0; ks < 2; ++ks) { qb[ks] = *(const LAS bf16x8*)(Qs + t * 72 + ks * 32 + fq * 8); sb[ks] = *(const LAS bf16x8*)(SQ + t * 72 + ks * 32 + fq * 8); }
; #pragma unroll
;       for (int vv = 0; vv < 4; ++vv) { const int vs = (wave & 1) * 4 + vv; f32x4 inter = {0.f, 0.f, 0.f, 0.f}, intra = {0.f, 0.f, 0.f, 0.f};
; #pragma unroll
;           for (int ks = 0; ks < 2; ++ks) { const bf16x8 ca = *(const LAS bf16x8*)(Cs + (vs * 16 + fr) * 72 + ks * 32 + fq * 8), va = *(const LAS bf16x8*)(VT + (vs * 16 + fr) * 72 + ks * 32 + fq * 8);
;               inter = __builtin_amdgcn_mfma_f32_16x16x32_bf16(ca, qb[ks], inter, 0, 0, 0);
;               intra = __builtin_amdgcn_mfma_f32_16x16x32_bf16(va, sb[ks], intra, 0, 0, 0); }
;           const int v0 = vs * 16 + fq * 4;
;           const bf16_t* prow = proj + (size_t)(t0 + t) * NP + h * 128 + v0;
;           const u32x2 op = *(const u32x2*)(prow + O_CO), zz = *(const u32x2*)(prow + O_CZ);
;           const float o0 = sigmoidf_(bflo(op.x)) * (wi * inter[0] + intra[0]) * inv * siluf_(bflo(zz.x));
;           const float o1 = sigmoidf_(bfhi(op.x)) * (wi * inter[1] + intra[1]) * inv * siluf_(bfhi(zz.x));
;           const float o2 = sigmoidf_(bflo(op.y)) * (wi * inter[2] + intra[2]) * inv * siluf_(bflo(zz.y));
;           const float o3 = sigmoidf_(bfhi(op.y)) * (wi * inter[3] + intra[3]) * inv * siluf_(bfhi(zz.y));
;           u32x2 w; w.x = cvt_pk_bf16(o0, o1); w.y = cvt_pk_bf16(o2, o3);
;           *(u32x2*)((bf16_t*)(P->ws + W_YS) + (size_t)(t0 + t) * DM + 1024 + h * 128 + v0) = w; } }
.LBB0_1108:
	s_or_b64 exec, exec, s[20:21]
	v_lshlrev_b32_e32 v2, 2, v19
	v_add_u32_e32 v5, 0, v2
	v_add_u32_e32 v2, v5, v2
	s_waitcnt lgkmcnt(0)
	s_barrier
	ds_read2st64_b32 v[28:29], v5 offset0:2 offset1:3
	ds_read_b32 v6, v5 offset:1280
	ds_read_b64 v[2:3], v2 offset:1536
	s_movk_i32 s20, 0x8c
	v_lshlrev_b32_e32 v4, 3, v10
	s_lshl_b32 s38, s30, 1
	s_add_i32 s82, s82, s56
	s_waitcnt lgkmcnt(0)
	v_fma_f32 v2, v29, v6, v2
	v_add_f32_e32 v2, v2, v3
	v_mul_f32_e32 v3, 0xbfb8aa3b, v28
	v_exp_f32_e32 v3, v3
	v_and_b32_e32 v28, 64, v18
	v_and_b32_e32 v18, 0x4f, v18
	v_mul_u32_u24_e32 v18, 0x48, v18
	v_max_f32_e64 v20, |v2|, v3
	v_mul_lo_u32 v2, v19, s20
	v_div_scale_f32 v21, s[20:21], v20, v20, 1.0
	v_rcp_f32_e32 v22, v21
	v_lshlrev_b32_e32 v3, 1, v4
	v_add3_u32 v6, v5, v2, v3
	v_lshl_add_u32 v31, v18, 1, v26
	v_fma_f32 v23, -v21, v22, 1.0
	v_fmac_f32_e32 v22, v23, v22
	v_div_scale_f32 v23, vcc, 1.0, v20, 1.0
	v_mul_f32_e32 v24, v23, v22
	v_fma_f32 v25, -v21, v24, v23
	v_fmac_f32_e32 v24, v25, v22
	v_fma_f32 v21, -v21, v24, v23
	v_div_fmas_f32 v21, v21, v22, v24
	v_div_fixup_f32 v30, v21, v20, 1.0
	v_add_u32_e32 v20, s83, v19
	v_ashrrev_i32_e32 v21, 31, v20
	v_mov_b64_e32 v[22:23], s[52:53]
	v_mad_i64_i32 v[22:23], s[20:21], v20, s26, v[22:23]
	v_lshlrev_b64 v[20:21], 12, v[20:21]
	v_lshl_add_u64 v[20:21], s[34:35], 0, v[20:21]
	ds_read_b128 v[10:13], v6 offset:2048
	ds_read_b128 v[14:17], v6 offset:20480
	ds_read_b128 v[2:5], v6 offset:2112
	ds_read_b128 v[6:9], v6 offset:20544
	v_lshl_add_u64 v[32:33], v[22:23], 0, s[38:39]
	v_lshl_add_u64 v[34:35], v[20:21], 0, s[38:39]
	ds_read_b128 v[18:21], v31 offset:48128
	ds_read_b128 v[22:25], v31 offset:29696
	v_or_b32_e32 v0, v0, v28
	s_waitcnt lgkmcnt(1)
	v_mfma_f32_16x16x32_bf16 v[18:21], v[18:21], v[10:13], 0
	ds_read_b128 v[36:39], v31 offset:48192
	ds_read_b128 v[40:43], v31 offset:29760
	v_lshlrev_b32_e32 v0, 1, v0
	v_lshl_add_u64 v[32:33], v[32:33], 0, v[0:1]
	v_add_co_u32_e32 v32, vcc, s4, v32
	s_waitcnt lgkmcnt(1)
	v_mfma_f32_16x16x32_bf16 v[18:21], v[36:39], v[2:5], v[18:21]
	v_addc_co_u32_e32 v33, vcc, 0, v33, vcc
	global_load_dwordx2 v[38:39], v[32:33], off offset:2320
	global_load_dwordx2 v[36:37], v[32:33], off offset:3344
	global_load_dwordx2 v[90:91], v[32:33], off offset:2352
	global_load_dwordx2 v[92:93], v[32:33], off offset:3376
	global_load_dwordx2 v[94:95], v[32:33], off offset:2384
	global_load_dwordx2 v[96:97], v[32:33], off offset:3408
	global_load_dwordx2 v[98:99], v[32:33], off offset:2416
	global_load_dwordx2 v[106:107], v[32:33], off offset:3440
	v_mfma_f32_16x16x32_bf16 v[22:25], v[22:25], v[14:17], 0
	s_mov_b32 s20, 0x39be2000
	s_add_i32 s81, s81, s69
	s_waitcnt vmcnt(1)
	v_lshlrev_b32_e32 v31, 16, v38
	v_mul_f32_e32 v31, 0xbfb8aa3b, v31
	v_exp_f32_e32 v31, v31
	s_waitcnt lgkmcnt(0)
	v_mfma_f32_16x16x32_bf16 v[22:25], v[40:43], v[6:9], v[22:25]
	s_waitcnt vmcnt(0)
	v_lshlrev_b32_e32 v41, 16, v36
	v_lshl_add_u64 v[42:43], v[34:35], 0, v[0:1]
	v_add_f32_e32 v31, 1.0, v31
	v_rcp_f32_e32 v31, v31
	v_or_b32_e32 v0, v28, v27
	s_nop 1
	v_fma_f32 v18, v29, v18, v22
	v_fma_f32 v19, v29, v19, v23
	v_mul_f32_e32 v40, v18, v31
	v_mul_f32_e32 v18, 0xbfb8aa3b, v41
	v_exp_f32_e32 v18, v18
	v_fmac_f32_e32 v25, v29, v21
	v_add_f32_e32 v18, 1.0, v18
	v_rcp_f32_e32 v31, v18
	v_and_b32_e32 v18, 0xffff0000, v38
	v_mul_f32_e32 v18, 0xbfb8aa3b, v18
	v_exp_f32_e32 v18, v18
	v_pk_mul_f32 v[40:41], v[30:31], v[40:41]
	v_add_f32_e32 v18, 1.0, v18
	v_rcp_f32_e32 v18, v18
	v_mul_f32_e32 v22, v40, v41
	v_mul_f32_e32 v18, v19, v18
	v_and_b32_e32 v19, 0xffff0000, v36
	v_mul_f32_e32 v23, 0xbfb8aa3b, v19
	v_exp_f32_e32 v23, v23
	s_nop 0
	v_add_f32_e32 v23, 1.0, v23
	v_rcp_f32_e32 v31, v23
	s_nop 0
	v_pk_mul_f32 v[18:19], v[30:31], v[18:19]
	s_nop 0
	v_mul_f32_e32 v23, v18, v19
	v_lshlrev_b32_e32 v18, 16, v39
	v_mul_f32_e32 v18, 0xbfb8aa3b, v18
	v_exp_f32_e32 v18, v18
	v_fma_f32 v19, v29, v20, v24
	v_add_f32_e32 v18, 1.0, v18
	v_rcp_f32_e32 v18, v18
	s_nop 0
	v_mul_f32_e32 v18, v19, v18
	v_lshlrev_b32_e32 v19, 16, v37
	v_mul_f32_e32 v20, 0xbfb8aa3b, v19
	v_exp_f32_e32 v20, v20
	s_nop 0
	v_add_f32_e32 v20, 1.0, v20
	v_rcp_f32_e32 v31, v20
	s_nop 0
	v_pk_mul_f32 v[18:19], v[30:31], v[18:19]
	s_nop 0
	v_mul_f32_e32 v20, v18, v19
	v_and_b32_e32 v18, 0xffff0000, v39
	v_mul_f32_e32 v18, 0xbfb8aa3b, v18
	v_and_b32_e32 v19, 0xffff0000, v37
	v_exp_f32_e32 v18, v18
	v_mul_f32_e32 v21, 0xbfb8aa3b, v19
	v_exp_f32_e32 v21, v21
	v_add_f32_e32 v18, 1.0, v18
	v_rcp_f32_e32 v18, v18
	v_add_f32_e32 v21, 1.0, v21
	v_rcp_f32_e32 v31, v21
	v_mul_f32_e32 v18, v25, v18
	v_pk_mul_f32 v[18:19], v[30:31], v[18:19]
	s_nop 0
	v_mul_f32_e32 v19, v18, v19
	s_nop 0
	v_cvt_pk_bf16_f32 v18, v22, v23
	s_nop 0
	v_cvt_pk_bf16_f32 v19, v20, v19
	v_add_co_u32_e32 v20, vcc, s20, v42
	s_mov_b64 s[20:21], 0x39be2000
	s_nop 0
	v_addc_co_u32_e32 v21, vcc, 0, v43, vcc
	global_store_dwordx2 v[20:21], v[18:19], off
	v_or_b32_e32 v18, 16, v0
	v_mul_u32_u24_e32 v18, 0x48, v18
	v_lshl_add_u32 v27, v18, 1, v26
	ds_read_b128 v[18:21], v27 offset:48128
	ds_read_b128 v[22:25], v27 offset:29696
	s_waitcnt lgkmcnt(1)
	v_mfma_f32_16x16x32_bf16 v[18:21], v[18:21], v[10:13], 0
	ds_read_b128 v[34:37], v27 offset:48192
	ds_read_b128 v[38:41], v27 offset:29760
	s_waitcnt lgkmcnt(1)
	v_mfma_f32_16x16x32_bf16 v[18:21], v[34:37], v[2:5], v[18:21]
	v_mov_b32_e32 v34, v90
	v_mov_b32_e32 v35, v91
	v_mov_b32_e32 v36, v92
	v_mov_b32_e32 v37, v93
	v_lshlrev_b32_e32 v27, 16, v34
	v_mul_f32_e32 v27, 0xbfb8aa3b, v27
	v_mfma_f32_16x16x32_bf16 v[22:25], v[22:25], v[14:17], 0
	v_exp_f32_e32 v27, v27
	s_nop 0
	v_add_f32_e32 v27, 1.0, v27
	s_waitcnt lgkmcnt(0)
; #define LAS __attribute__((address_space(3)))
; __device__ __forceinline__ float bflo(unsigned u) { return __uint_as_float(u << 16); }
; __device__ __forceinline__ float bfhi(unsigned u) { return __uint_as_float(u & 0xffff0000u); }
; __device__ __forceinline__ unsigned cvt_pk_bf16(float lo, float hi) { unsigned r; asm volatile("s_nop 0\n\tv_cvt_pk_bf16_f32 %0, %1, %2" : "=v"(r) : "v"(lo), "v"(hi)); return r; }
; __device__ __forceinline__ float sigmoidf_(float x) { return __builtin_amdgcn_rcpf(1.f + __expf(-x)); }
; __device__ __forceinline__ float siluf_(float x) { return x * sigmoidf_(x); }
; __device__ __forceinline__ void c3_item(KP P, int l, int item, LAS unsigned char* lds) {
;     ...
;       for (int vv = 0; vv < 4; ++vv) { const int vs = (wave & 1) * 4 + vv; f32x4 inter = {0.f, 0.f, 0.f, 0.f}, intra = {0.f, 0.f, 0.f, 0.f};
; #pragma unroll
;           for (int ks = 0; ks < 2; ++ks) { const bf16x8 ca = *(const LAS bf16x8*)(Cs + (vs * 16 + fr) * 72 + ks * 32 + fq * 8), va = *(const LAS bf16x8*)(VT + (vs * 16 + fr) * 72 + ks * 32 + fq * 8);
;               inter = __builtin_amdgcn_mfma_f32_16x16x32_bf16(ca, qb[ks], inter, 0, 0, 0);
;               intra = __builtin_amdgcn_mfma_f32_16x16x32_bf16(va, sb[ks], intra, 0, 0, 0); }
;           const int v0 = vs * 16 + fq * 4;
;           const bf16_t* prow = proj + (size_t)(t0 + t) * NP + h * 128 + v0;
;           const u32x2 op = *(const u32x2*)(prow + O_CO), zz = *(const u32x2*)(prow + O_CZ);
;           const float o0 = sigmoidf_(bflo(op.x)) * (wi * inter[0] + intra[0]) * inv * siluf_(bflo(zz.x));
;           const float o1 = sigmoidf_(bfhi(op.x)) * (wi * inter[1] + intra[1]) * inv * siluf_(bfhi(zz.x));
;           const float o2 = sigmoidf_(bflo(op.y)) * (wi * inter[2] + intra[2]) * inv * siluf_(bflo(zz.y));
;           const float o3 = sigmoidf_(bfhi(op.y)) * (wi * inter[3] + intra[3]) * inv * siluf_(bfhi(zz.y));
;           u32x2 w; w.x = cvt_pk_bf16(o0, o1); w.y = cvt_pk_bf16(o2, o3);
;           *(u32x2*)((bf16_t*)(P->ws + W_YS) + (size_t)(t0 + t) * DM + 1024 + h * 128 + v0) = w; } }
	v_mfma_f32_16x16x32_bf16 v[22:25], v[38:41], v[6:9], v[22:25]
	v_rcp_f32_e32 v27, v27
	s_nop 0
	v_lshlrev_b32_e32 v39, 16, v36
	s_nop 4
	v_fma_f32 v18, v29, v18, v22
	v_mul_f32_e32 v38, v18, v27
	v_mul_f32_e32 v18, 0xbfb8aa3b, v39
	v_exp_f32_e32 v18, v18
	v_fma_f32 v19, v29, v19, v23
	v_fmac_f32_e32 v25, v29, v21
	v_add_f32_e32 v18, 1.0, v18
	v_rcp_f32_e32 v31, v18
	v_and_b32_e32 v18, 0xffff0000, v34
	v_mul_f32_e32 v18, 0xbfb8aa3b, v18
	v_exp_f32_e32 v18, v18
	v_pk_mul_f32 v[38:39], v[30:31], v[38:39]
	v_add_f32_e32 v18, 1.0, v18
	v_rcp_f32_e32 v18, v18
	v_mul_f32_e32 v22, v38, v39
	v_mul_f32_e32 v18, v19, v18
	v_and_b32_e32 v19, 0xffff0000, v36
	v_mul_f32_e32 v23, 0xbfb8aa3b, v19
	v_exp_f32_e32 v23, v23
	s_nop 0
	v_add_f32_e32 v23, 1.0, v23
	v_rcp_f32_e32 v31, v23
	s_nop 0
	v_pk_mul_f32 v[18:19], v[30:31], v[18:19]
	s_nop 0
	v_mul_f32_e32 v23, v18, v19
	v_lshlrev_b32_e32 v18, 16, v35
	v_mul_f32_e32 v18, 0xbfb8aa3b, v18
	v_exp_f32_e32 v18, v18
	v_fma_f32 v19, v29, v20, v24
	v_add_f32_e32 v18, 1.0, v18
	v_rcp_f32_e32 v18, v18
	s_nop 0
	v_mul_f32_e32 v18, v19, v18
	v_lshlrev_b32_e32 v19, 16, v37
	v_mul_f32_e32 v20, 0xbfb8aa3b, v19
	v_exp_f32_e32 v20, v20
	s_nop 0
	v_add_f32_e32 v20, 1.0, v20
	v_rcp_f32_e32 v31, v20
	s_nop 0
	v_pk_mul_f32 v[18:19], v[30:31], v[18:19]
	s_nop 0
	v_mul_f32_e32 v20, v18, v19
	v_and_b32_e32 v18, 0xffff0000, v35
	v_mul_f32_e32 v18, 0xbfb8aa3b, v18
	v_and_b32_e32 v19, 0xffff0000, v37
	v_exp_f32_e32 v18, v18
	v_mul_f32_e32 v21, 0xbfb8aa3b, v19
	v_exp_f32_e32 v21, v21
	v_lshl_add_u64 v[34:35], v[42:43], 0, s[20:21]
	v_add_f32_e32 v18, 1.0, v18
	v_rcp_f32_e32 v18, v18
	v_add_f32_e32 v21, 1.0, v21
	v_rcp_f32_e32 v31, v21
	v_readlane_b32 s20, v255, 18
	v_mul_f32_e32 v18, v25, v18
	v_readlane_b32 s21, v255, 19
	v_pk_mul_f32 v[18:19], v[30:31], v[18:19]
	s_add_u32 s24, s24, s20
	v_mul_f32_e32 v19, v18, v19
	s_nop 0
	v_cvt_pk_bf16_f32 v18, v22, v23
	s_nop 0
	v_cvt_pk_bf16_f32 v19, v20, v19
	global_store_dwordx2 v[34:35], v[18:19], off offset:32
	v_or_b32_e32 v18, 32, v0
	v_mul_u32_u24_e32 v18, 0x48, v18
	v_lshl_add_u32 v27, v18, 1, v26
	ds_read_b128 v[18:21], v27 offset:48128
	ds_read_b128 v[22:25], v27 offset:29696
	s_waitcnt lgkmcnt(1)
	v_mfma_f32_16x16x32_bf16 v[18:21], v[18:21], v[10:13], 0
	ds_read_b128 v[36:39], v27 offset:48192
	ds_read_b128 v[40:43], v27 offset:29760
	v_or_b32_e32 v0, 48, v0
	v_mul_u32_u24_e32 v0, 0x48, v0
	s_waitcnt lgkmcnt(1)
	v_mfma_f32_16x16x32_bf16 v[18:21], v[36:39], v[2:5], v[18:21]
	v_mov_b32_e32 v38, v94
	v_mov_b32_e32 v39, v95
	v_mov_b32_e32 v36, v96
	v_mov_b32_e32 v37, v97
	v_lshl_add_u32 v0, v0, 1, v26
	s_addc_u32 s25, s25, s21
	v_mfma_f32_16x16x32_bf16 v[22:25], v[22:25], v[14:17], 0
	v_readlane_b32 s20, v255, 35
	v_readlane_b32 s21, v255, 36
	s_add_u32 s6, s6, s20
	s_waitcnt lgkmcnt(0)
; #define LAS __attribute__((address_space(3)))
; __device__ __forceinline__ float bflo(unsigned u) { return __uint_as_float(u << 16); }
; __device__ __forceinline__ float bfhi(unsigned u) { return __uint_as_float(u & 0xffff0000u); }
; __device__ __forceinline__ unsigned cvt_pk_bf16(float lo, float hi) { unsigned r; asm volatile("s_nop 0\n\tv_cvt_pk_bf16_f32 %0, %1, %2" : "=v"(r) : "v"(lo), "v"(hi)); return r; }
; __device__ __forceinline__ float sigmoidf_(float x) { return __builtin_amdgcn_rcpf(1.f + __expf(-x)); }
; __device__ __forceinline__ float siluf_(float x) { return x * sigmoidf_(x); }
; __device__ __forceinline__ void c3_item(KP P, int l, int item, LAS unsigned char* lds) {
;     ...
;       for (int vv = 0; vv < 4; ++vv) { const int vs = (wave & 1) * 4 + vv; f32x4 inter = {0.f, 0.f, 0.f, 0.f}, intra = {0.f, 0.f, 0.f, 0.f};
; #pragma unroll
;           for (int ks = 0; ks < 2; ++ks) { const bf16x8 ca = *(const LAS bf16x8*)(Cs + (vs * 16 + fr) * 72 + ks * 32 + fq * 8), va = *(const LAS bf16x8*)(VT + (vs * 16 + fr) * 72 + ks * 32 + fq * 8);
;               inter = __builtin_amdgcn_mfma_f32_16x16x32_bf16(ca, qb[ks], inter, 0, 0, 0);
;               intra = __builtin_amdgcn_mfma_f32_16x16x32_bf16(va, sb[ks], intra, 0, 0, 0); }
;           const int v0 = vs * 16 + fq * 4;
;           const bf16_t* prow = proj + (size_t)(t0 + t) * NP + h * 128 + v0;
;           const u32x2 op = *(const u32x2*)(prow + O_CO), zz = *(const u32x2*)(prow + O_CZ);
;           const float o0 = sigmoidf_(bflo(op.x)) * (wi * inter[0] + intra[0]) * inv * siluf_(bflo(zz.x));
;           const float o1 = sigmoidf_(bfhi(op.x)) * (wi * inter[1] + intra[1]) * inv * siluf_(bfhi(zz.x));
;           const float o2 = sigmoidf_(bflo(op.y)) * (wi * inter[2] + intra[2]) * inv * siluf_(bflo(zz.y));
;           const float o3 = sigmoidf_(bfhi(op.y)) * (wi * inter[3] + intra[3]) * inv * siluf_(bfhi(zz.y));
;           u32x2 w; w.x = cvt_pk_bf16(o0, o1); w.y = cvt_pk_bf16(o2, o3);
;           *(u32x2*)((bf16_t*)(P->ws + W_YS) + (size_t)(t0 + t) * DM + 1024 + h * 128 + v0) = w; } }
;     __syncthreads();
	v_mfma_f32_16x16x32_bf16 v[22:25], v[40:43], v[6:9], v[22:25]
	s_addc_u32 s7, s7, s21
	s_add_i32 s80, s80, s79
	s_cmpk_gt_i32 s82, 0x1ff
	s_nop 0
	v_lshlrev_b32_e32 v27, 16, v38
	v_mul_f32_e32 v27, 0xbfb8aa3b, v27
	v_exp_f32_e32 v27, v27
	s_nop 0
	v_fma_f32 v18, v29, v18, v22
	s_nop 0
	v_lshlrev_b32_e32 v41, 16, v36
	v_fma_f32 v19, v29, v19, v23
	v_add_f32_e32 v27, 1.0, v27
	v_rcp_f32_e32 v27, v27
	v_fmac_f32_e32 v25, v29, v21
	v_mul_f32_e32 v40, v18, v27
	v_mul_f32_e32 v18, 0xbfb8aa3b, v41
	v_exp_f32_e32 v18, v18
	s_nop 0
	v_add_f32_e32 v18, 1.0, v18
	v_rcp_f32_e32 v31, v18
	v_and_b32_e32 v18, 0xffff0000, v38
	v_mul_f32_e32 v18, 0xbfb8aa3b, v18
	v_exp_f32_e32 v18, v18
	v_pk_mul_f32 v[40:41], v[30:31], v[40:41]
	v_add_f32_e32 v18, 1.0, v18
	v_rcp_f32_e32 v18, v18
	v_mul_f32_e32 v22, v40, v41
	v_mul_f32_e32 v18, v19, v18
	v_and_b32_e32 v19, 0xffff0000, v36
	v_mul_f32_e32 v23, 0xbfb8aa3b, v19
	v_exp_f32_e32 v23, v23
	s_nop 0
	v_add_f32_e32 v23, 1.0, v23
	v_rcp_f32_e32 v31, v23
	s_nop 0
	v_pk_mul_f32 v[18:19], v[30:31], v[18:19]
	s_nop 0
	v_mul_f32_e32 v23, v18, v19
	v_lshlrev_b32_e32 v18, 16, v39
	v_mul_f32_e32 v18, 0xbfb8aa3b, v18
	v_exp_f32_e32 v18, v18
	v_fma_f32 v19, v29, v20, v24
	v_add_f32_e32 v18, 1.0, v18
	v_rcp_f32_e32 v18, v18
	s_nop 0
	v_mul_f32_e32 v18, v19, v18
	v_lshlrev_b32_e32 v19, 16, v37
	v_mul_f32_e32 v20, 0xbfb8aa3b, v19
	v_exp_f32_e32 v20, v20
	s_nop 0
	v_add_f32_e32 v20, 1.0, v20
	v_rcp_f32_e32 v31, v20
	s_nop 0
	v_pk_mul_f32 v[18:19], v[30:31], v[18:19]
	s_nop 0
	v_mul_f32_e32 v20, v18, v19
	v_and_b32_e32 v18, 0xffff0000, v39
	v_mul_f32_e32 v18, 0xbfb8aa3b, v18
	v_and_b32_e32 v19, 0xffff0000, v37
	v_exp_f32_e32 v18, v18
	v_mul_f32_e32 v21, 0xbfb8aa3b, v19
	v_exp_f32_e32 v21, v21
	v_add_f32_e32 v18, 1.0, v18
	v_rcp_f32_e32 v18, v18
	v_add_f32_e32 v21, 1.0, v21
	v_rcp_f32_e32 v31, v21
	v_mul_f32_e32 v18, v25, v18
	v_pk_mul_f32 v[18:19], v[30:31], v[18:19]
	s_nop 0
	v_mul_f32_e32 v19, v18, v19
	s_nop 0
	v_cvt_pk_bf16_f32 v18, v22, v23
	s_nop 0
	v_cvt_pk_bf16_f32 v19, v20, v19
	global_store_dwordx2 v[34:35], v[18:19], off offset:64
	ds_read_b128 v[18:21], v0 offset:48128
	ds_read_b128 v[22:25], v0 offset:29696
	s_waitcnt lgkmcnt(1)
	v_mfma_f32_16x16x32_bf16 v[10:13], v[18:21], v[10:13], 0
	s_waitcnt lgkmcnt(0)
	v_mfma_f32_16x16x32_bf16 v[14:17], v[22:25], v[14:17], 0
	ds_read_b128 v[18:21], v0 offset:48192
	ds_read_b128 v[22:25], v0 offset:29760
	s_waitcnt lgkmcnt(1)
	v_mfma_f32_16x16x32_bf16 v[2:5], v[18:21], v[2:5], v[10:13]
	s_nop 2
	v_mov_b32_e32 v10, v98
	v_mov_b32_e32 v11, v99
	v_mov_b32_e32 v12, v106
	v_mov_b32_e32 v13, v107
	v_lshlrev_b32_e32 v0, 16, v10
	v_mul_f32_e32 v0, 0xbfb8aa3b, v0
	v_exp_f32_e32 v0, v0
	s_waitcnt lgkmcnt(0)
	v_mfma_f32_16x16x32_bf16 v[6:9], v[22:25], v[6:9], v[14:17]
	v_add_f32_e32 v0, 1.0, v0
	v_rcp_f32_e32 v0, v0
	s_nop 0
	v_lshlrev_b32_e32 v15, 16, v12
	s_nop 3
	v_fma_f32 v2, v29, v2, v6
	v_fma_f32 v3, v29, v3, v7
	v_mul_f32_e32 v14, v2, v0
	v_and_b32_e32 v2, 0xffff0000, v10
	v_mul_f32_e32 v2, 0xbfb8aa3b, v2
	v_exp_f32_e32 v2, v2
	v_mul_f32_e32 v0, 0xbfb8aa3b, v15
	v_exp_f32_e32 v0, v0
	v_fmac_f32_e32 v9, v29, v5
	v_add_f32_e32 v2, 1.0, v2
	v_rcp_f32_e32 v2, v2
	v_add_f32_e32 v0, 1.0, v0
	v_rcp_f32_e32 v31, v0
	v_mul_f32_e32 v2, v3, v2
	v_and_b32_e32 v3, 0xffff0000, v12
	v_mul_f32_e32 v6, 0xbfb8aa3b, v3
	v_exp_f32_e32 v6, v6
	v_pk_mul_f32 v[14:15], v[30:31], v[14:15]
	v_add_f32_e32 v6, 1.0, v6
	v_rcp_f32_e32 v31, v6
	v_mul_f32_e32 v0, v14, v15
	v_pk_mul_f32 v[2:3], v[30:31], v[2:3]
	s_nop 0
	v_mul_f32_e32 v6, v2, v3
	v_lshlrev_b32_e32 v2, 16, v11
	v_mul_f32_e32 v2, 0xbfb8aa3b, v2
	v_exp_f32_e32 v2, v2
	v_fma_f32 v3, v29, v4, v8
	v_add_f32_e32 v2, 1.0, v2
	v_rcp_f32_e32 v2, v2
	s_nop 0
	v_mul_f32_e32 v2, v3, v2
	v_lshlrev_b32_e32 v3, 16, v13
	v_mul_f32_e32 v4, 0xbfb8aa3b, v3
	v_exp_f32_e32 v4, v4
	s_nop 0
	v_add_f32_e32 v4, 1.0, v4
	v_rcp_f32_e32 v31, v4
	s_nop 0
	v_pk_mul_f32 v[2:3], v[30:31], v[2:3]
	s_nop 0
	v_mul_f32_e32 v4, v2, v3
	v_and_b32_e32 v2, 0xffff0000, v11
	v_mul_f32_e32 v2, 0xbfb8aa3b, v2
	v_and_b32_e32 v3, 0xffff0000, v13
	v_exp_f32_e32 v2, v2
	v_mul_f32_e32 v5, 0xbfb8aa3b, v3
	v_exp_f32_e32 v5, v5
	v_add_f32_e32 v2, 1.0, v2
	v_rcp_f32_e32 v2, v2
	v_add_f32_e32 v5, 1.0, v5
	v_rcp_f32_e32 v31, v5
	v_mul_f32_e32 v2, v9, v2
	v_pk_mul_f32 v[2:3], v[30:31], v[2:3]
	s_nop 0
	v_mul_f32_e32 v3, v2, v3
	s_nop 0
	v_cvt_pk_bf16_f32 v2, v0, v6
	s_nop 0
	v_cvt_pk_bf16_f32 v3, v4, v3
	global_store_dwordx2 v[34:35], v[2:3], off offset:96
	s_barrier
	s_cbranch_scc1 .LBB0_1153
